# v17 + P2/P3 mixer first/last ordering keyed on blockIdx bit 3 (both kinds on every XCD) instead of bit 0
# speedup vs baseline: 1.0178x; 1.0032x over previous
; __global__ void __launch_bounds__(512, 2) fwd_kernel(Args a) {
;     ...
;     if (IN(2)) for (int rep_ = 0; rep_ < 1 + ((DUPMASK >> 2) & 1); ++rep_) { if (rep_) xcd_barrier(bar);
;         if (bx & 1) for (int u = bx; u < 256; u += G) ret_decode_unit(lds, Z, state0, out + O_SS, MIX, rng, u >> 2, u & 3, tid);
;         for (int u = bx; u < 256; u += G) ret_step1(lds, Z, KV, u >> 2, u & 3, tid);
;         if (!(bx & 1)) for (int u = bx; u < 256; u += G) ret_decode_unit(lds, Z, state0, out + O_SS, MIX, rng, u >> 2, u & 3, tid);
;     }
.LBB0_226:
	s_cmp_lt_i32 s62, 3
	s_cselect_b64 s[2:3], -1, 0
	s_add_u32 s56, s60, 0x8000000
	s_addc_u32 s57, s61, 0
	s_add_u32 s4, s60, 0xfc00000
	s_addc_u32 s5, s61, 0
	v_writelane_b32 v254, s4, 23
	s_and_b64 s[10:11], s[2:3], s[0:1]
	s_andn2_b64 vcc, exec, s[10:11]
	v_writelane_b32 v254, s5, 24
	v_lshrrev_b32_e32 v252, 6, v253
	v_cmp_gt_u32_e64 s[0:1], 64, v253
	s_cbranch_vccnz .LBB0_250
	s_bitcmp0_b32 s92, 3
	v_readlane_b32 s68, v254, 7
	s_cselect_b64 s[14:15], -1, 0
	s_cmpk_gt_i32 s92, 0xff
	v_readlane_b32 s82, v254, 21
	v_lshlrev_b32_e32 v0, 2, v253
	s_cselect_b64 s[2:3], -1, 0
	v_readlane_b32 s83, v254, 22
	s_add_u32 s12, s82, 0x5220000
	v_and_b32_e32 v147, 0xfc, v0
	v_readlane_b32 s72, v254, 11
	v_readlane_b32 s73, v254, 12
	s_addc_u32 s13, s83, 0
	s_movk_i32 s4, 0x100
	v_add_u32_e32 v146, 0, v0
	v_lshlrev_b32_e32 v20, 2, v147
	v_mov_b32_e32 v21, 0
	v_lshl_add_u32 v149, v252, 7, 0
	v_mul_u32_u24_e32 v0, 0x380, v252
	s_or_b64 s[2:3], s[14:15], s[2:3]
	s_mov_b32 s17, 0
	v_add_u32_e32 v144, 0x900, v253
	v_add_u32_e32 v145, 0xd00, v253
	v_cmp_gt_u32_e64 s[6:7], s4, v253
	v_add_u32_e32 v148, 0, v20
	v_lshl_or_b32 v128, v252, 13, v147
	v_mov_b32_e32 v129, v21
	v_add3_u32 v150, v149, v0, v20
	v_lshl_add_u64 v[130:131], s[72:73], 0, v[20:21]
	s_and_b64 vcc, exec, s[2:3]
	v_readlane_b32 s69, v254, 8
	v_readlane_b32 s70, v254, 9
	v_readlane_b32 s71, v254, 10
	v_readlane_b32 s74, v254, 13
	v_readlane_b32 s75, v254, 14
	v_readlane_b32 s76, v254, 15
	v_readlane_b32 s77, v254, 16
	v_readlane_b32 s78, v254, 17
	v_readlane_b32 s79, v254, 18
	v_readlane_b32 s80, v254, 19
	v_readlane_b32 s81, v254, 20
	s_cbranch_vccnz .LBB0_236
	v_mbcnt_lo_u32_b32 v0, -1, 0
	v_mov_b32_e32 v30, 0x42800000
	v_mov_b32_e32 v31, 0x358637bd
	v_mbcnt_hi_u32_b32 v32, -1, v0
	s_mov_b32 s18, s92
	s_branch .LBB0_230

; __global__ void __launch_bounds__(512, 2) fwd_kernel(Args a) {
;     ...
;     if (IN(3)) for (int rep_ = 0; rep_ < 1 + ((DUPMASK >> 3) & 1); ++rep_) { if (rep_) xcd_barrier(bar);
;         if (tid < 256) ret_scan(KV, SP, out + O_SP, bx * 256 + tid, G * 256);
;         if (bx & 1) for (int u = bx; u < 256; u += G) attn_decode_unit(lds, Z, cache_k, cache_v, MIX, gq, gk, sinks, out + O_KS, out + O_VS, u >> 1, u & 1, tid);
;         for (int u = 256 + bx; u < 512; u += G) ret_decode_unit(lds, Z, state0, out + O_SS, MIX, rng, u >> 2, u & 3, tid);
;         if (!(bx & 1)) for (int u = bx; u < 256; u += G) attn_decode_unit(lds, Z, cache_k, cache_v, MIX, gq, gk, sinks, out + O_KS, out + O_VS, u >> 1, u & 1, tid);
;     }
.LBB0_310:
	v_readlane_b32 s0, v254, 39
	v_readlane_b32 s1, v254, 40
	s_or_b64 exec, exec, s[0:1]
	v_readlane_b32 s92, v254, 37
	s_bitcmp0_b32 s92, 3
	v_readlane_b32 s68, v254, 7
	s_cselect_b64 s[18:19], -1, 0
	s_cmpk_gt_i32 s92, 0xff
	v_readlane_b32 s82, v254, 21
	s_cselect_b64 s[4:5], -1, 0
	v_readlane_b32 s83, v254, 22
	s_add_u32 s14, s82, 0x4220000
	s_addc_u32 s15, s83, 0
	s_add_u32 s16, s82, 0x4a20000
	v_add_u32_e32 v3, 0x200, v253
	s_addc_u32 s17, s83, 0
	v_lshlrev_b32_e32 v0, 2, v253
	v_lshrrev_b32_e32 v42, 4, v3
	v_add_u32_e32 v3, 0x600, v253
	v_lshlrev_b32_e32 v8, 2, v152
	s_add_i32 s6, 0, 0x10a10
	v_lshrrev_b32_e32 v44, 4, v3
	v_add_u32_e32 v3, 0, v8
	v_add_u32_e32 v47, s6, v0
	s_movk_i32 s6, 0x10c
	s_add_i32 s7, 0, 0x11210
	v_and_b32_e32 v40, 60, v0
	v_lshrrev_b32_e32 v41, 4, v253
	v_mad_u32_u24 v48, v152, s6, v3
	s_movk_i32 s6, 0x210
	v_mov_b32_e32 v4, s7
	v_readlane_b32 s69, v254, 8
	v_mov_b32_e32 v9, 0
	v_lshl_add_u32 v56, v40, 2, 0
	v_mul_u32_u24_e32 v1, 0x110, v41
	v_lshlrev_b32_e32 v2, 8, v41
	v_or_b32_e32 v43, 64, v41
	v_add_u32_e32 v46, 0x8910, v3
	v_mul_u32_u24_e32 v3, 0x210, v252
	v_mad_u32_u24 v50, v252, s6, v4
	s_or_b64 s[4:5], s[18:19], s[4:5]
	v_readlane_b32 s84, v254, 27
	v_readlane_b32 s86, v254, 29
	v_readlane_b32 s88, v254, 31
	v_readlane_b32 s90, v254, 35
	s_mov_b32 s21, 0
	v_mul_u32_u24_e32 v57, 0x110, v42
	v_lshlrev_b32_e32 v58, 8, v42
	v_lshlrev_b32_e32 v59, 8, v43
	v_mul_u32_u24_e32 v60, 0x110, v44
	v_lshlrev_b32_e32 v61, 8, v44
	v_cmp_gt_u32_e64 s[0:1], 64, v253
	v_lshl_add_u64 v[20:21], s[68:69], 0, v[8:9]
	v_add_u32_e32 v45, 0, v0
	v_cmp_eq_u32_e64 s[8:9], 1, v252
	v_lshl_add_u64 v[22:23], s[58:59], 0, v[8:9]
	v_mul_i32_i24_e32 v49, 0xfffffef4, v152
	v_add_u32_e32 v51, v50, v8
	v_cmp_eq_u32_e64 s[10:11], 0, v152
	v_and_b32_e32 v62, 0xfc, v0
	s_and_b64 vcc, exec, s[4:5]
	v_lshl_add_u32 v52, v252, 8, 0
	v_add_u32_e32 v53, 0, v3
	v_lshlrev_b32_e32 v24, 1, v152
	v_add_u32_e32 v54, v56, v1
	v_add_u32_e32 v55, v56, v2
	v_readlane_b32 s85, v254, 28
	v_readlane_b32 s87, v254, 30
	v_readlane_b32 s89, v254, 32
	v_readlane_b32 s91, v254, 36
	v_readlane_b32 s93, v254, 38
	v_readlane_b32 s70, v254, 9
	v_readlane_b32 s71, v254, 10
	v_readlane_b32 s72, v254, 11
	v_readlane_b32 s73, v254, 12
	v_readlane_b32 s74, v254, 13
	v_readlane_b32 s75, v254, 14
	v_readlane_b32 s76, v254, 15
	v_readlane_b32 s77, v254, 16
	v_readlane_b32 s78, v254, 17
	v_readlane_b32 s79, v254, 18
	v_readlane_b32 s80, v254, 19
	v_readlane_b32 s81, v254, 20
	s_cbranch_vccnz .LBB0_325
	v_mbcnt_lo_u32_b32 v0, -1, 0
	v_mbcnt_hi_u32_b32 v0, -1, v0
	v_and_b32_e32 v1, 64, v0
	v_add_u32_e32 v1, 64, v1
	v_xor_b32_e32 v2, 1, v0
	v_cmp_lt_i32_e32 vcc, v2, v1
	s_movk_i32 s22, 0xfe00
	s_mov_b32 s23, -1
	v_cndmask_b32_e32 v2, v0, v2, vcc
	v_lshlrev_b32_e32 v14, 2, v2
	v_xor_b32_e32 v2, 2, v0
	v_cmp_lt_i32_e32 vcc, v2, v1
	v_mov_b32_e32 v27, 0x358637bd
	s_mov_b32 s12, 0x800000
	v_cndmask_b32_e32 v2, v0, v2, vcc
	v_lshlrev_b32_e32 v15, 2, v2
	v_xor_b32_e32 v2, 4, v0
	v_cmp_lt_i32_e32 vcc, v2, v1
	s_mov_b32 s13, s92
	s_nop 0
	v_cndmask_b32_e32 v2, v0, v2, vcc
	v_lshlrev_b32_e32 v16, 2, v2
	v_xor_b32_e32 v2, 8, v0
	v_cmp_lt_i32_e32 vcc, v2, v1
	s_nop 1
	v_cndmask_b32_e32 v2, v0, v2, vcc
	v_lshlrev_b32_e32 v17, 2, v2
	v_xor_b32_e32 v2, 16, v0
	v_cmp_lt_i32_e32 vcc, v2, v1
	s_nop 1
	v_cndmask_b32_e32 v2, v0, v2, vcc
	v_lshlrev_b32_e32 v18, 2, v2
	v_xor_b32_e32 v2, 32, v0
	v_cmp_lt_i32_e32 vcc, v2, v1
	s_nop 1
	v_cndmask_b32_e32 v0, v0, v2, vcc
	v_lshlrev_b32_e32 v19, 2, v0
	v_add_u32_e32 v0, 0, v62
	v_add_u32_e32 v26, 0x8910, v0
